# XCD-local barriers after phases 6,7,9,10,11 (skip cross-XCD stage when placement verified); ffn/ple norm rows remapped to owning XCD
# speedup vs baseline: 1.1672x; 1.0158x over previous
.LBB0_14:
	s_add_u32 s96, s88, 0xf000000
	s_addc_u32 s97, s89, 0
	s_getreg_b32 s6, hwreg(HW_REG_XCC_ID, 0, 4)
	s_and_saveexec_b64 s[2:3], s[80:81]
	s_cbranch_execz .LBB0_17
	s_mov_b64 s[4:5], exec
	v_mbcnt_lo_u32_b32 v0, s4, 0
	v_mbcnt_hi_u32_b32 v0, s5, v0
	v_cmp_eq_u32_e32 vcc, 0, v0
	s_and_b64 s[8:9], exec, vcc
	s_mov_b64 exec, s[8:9]
	s_cbranch_execz .LBB0_17
	s_and_b32 s10, s6, 15
	s_lshl_b32 s10, 1, s10
	s_cmpk_lg_i32 s90, 0x200
	s_cselect_b32 s11, 0x100000, 0
	s_or_b32 s10, s10, s11
	s_and_b32 s11, s33, 7
	s_lshl_b32 s11, s11, 2
	v_mov_b32_e32 v0, s11
	v_mov_b32_e32 v1, s10
	global_atomic_or v1, v0, v1, s[96:97] offset:16 sc0
	s_waitcnt vmcnt(0)
	s_lshl_b32 s6, s6, 8
	s_and_b32 s6, s6, 0xf00
	s_bcnt1_i32_b64 s4, s[4:5]
	v_mov_b32_e32 v0, s6
	v_mov_b32_e32 v1, s4
	global_atomic_add v0, v1, s[96:97] offset:1024

.LBB0_302:
	s_cmp_eq_u32 s8, 0
	s_cselect_b64 vcc, -1, 0
	s_cmp_eq_u32 s8, 1
	v_cndmask_b32_e32 v16, 0, v0, vcc
	s_cselect_b64 vcc, -1, 0
	s_cmp_eq_u32 s8, 2
	v_cndmask_b32_e32 v16, v16, v1, vcc
	s_cselect_b64 vcc, -1, 0
	s_cmp_eq_u32 s8, 3
	v_cndmask_b32_e32 v16, v16, v2, vcc
	s_cselect_b64 vcc, -1, 0
	s_cmp_eq_u32 s8, 4
	v_cndmask_b32_e32 v16, v16, v3, vcc
	s_cselect_b64 vcc, -1, 0
	s_cmp_eq_u32 s8, 5
	v_cndmask_b32_e32 v16, v16, v4, vcc
	s_cselect_b64 vcc, -1, 0
	s_cmp_eq_u32 s8, 6
	v_cndmask_b32_e32 v16, v16, v5, vcc
	s_cselect_b64 vcc, -1, 0
	s_cmp_eq_u32 s8, 7
	v_cndmask_b32_e32 v16, v16, v6, vcc
	s_cselect_b64 vcc, -1, 0
	s_cmp_eq_u32 s8, 8
	v_cndmask_b32_e32 v16, v16, v7, vcc
	s_cselect_b64 vcc, -1, 0
	s_cmp_eq_u32 s8, 9
	v_cndmask_b32_e32 v16, v16, v8, vcc
	s_cselect_b64 vcc, -1, 0
	s_cmp_eq_u32 s8, 10
	v_cndmask_b32_e32 v16, v16, v9, vcc
	s_cselect_b64 vcc, -1, 0
	s_cmp_eq_u32 s8, 11
	v_cndmask_b32_e32 v16, v16, v10, vcc
	s_cselect_b64 vcc, -1, 0
	s_cmp_eq_u32 s8, 12
	v_cndmask_b32_e32 v16, v16, v11, vcc
	s_cselect_b64 vcc, -1, 0
	s_cmp_eq_u32 s8, 13
	v_cndmask_b32_e32 v16, v16, v12, vcc
	s_cselect_b64 vcc, -1, 0
	s_cmp_eq_u32 s8, 14
	v_cndmask_b32_e32 v16, v16, v13, vcc
	s_cselect_b64 vcc, -1, 0
	s_cmp_eq_u32 s8, 15
	v_cndmask_b32_e32 v16, v16, v14, vcc
	s_cselect_b64 vcc, -1, 0
	v_cndmask_b32_e32 v16, v16, v15, vcc
	v_cmp_ne_u32_e32 vcc, 0, v0
	s_nop 1
	v_cndmask_b32_e64 v0, 0, 1, vcc
	v_cmp_ne_u32_e32 vcc, 0, v1
	s_nop 1
	v_addc_co_u32_e32 v0, vcc, 0, v0, vcc
	v_cmp_ne_u32_e32 vcc, 0, v2
	v_max_u32_e32 v2, 1, v16
	s_nop 0
	v_cndmask_b32_e64 v1, 0, 1, vcc
	v_cmp_ne_u32_e32 vcc, 0, v3
	s_nop 1
	v_addc_co_u32_e32 v0, vcc, v0, v1, vcc
	v_cmp_ne_u32_e32 vcc, 0, v4
	s_nop 1
	v_cndmask_b32_e64 v1, 0, 1, vcc
	v_cmp_ne_u32_e32 vcc, 0, v5
	s_nop 1
	v_addc_co_u32_e32 v0, vcc, v0, v1, vcc
	v_cmp_ne_u32_e32 vcc, 0, v6
	s_nop 1
	v_cndmask_b32_e64 v1, 0, 1, vcc
	v_cmp_ne_u32_e32 vcc, 0, v7
	s_nop 1
	v_addc_co_u32_e32 v0, vcc, v0, v1, vcc
	v_cmp_ne_u32_e32 vcc, 0, v8
	s_nop 1
	v_cndmask_b32_e64 v1, 0, 1, vcc
	v_cmp_ne_u32_e32 vcc, 0, v9
	s_nop 1
	v_addc_co_u32_e32 v0, vcc, v0, v1, vcc
	v_cmp_ne_u32_e32 vcc, 0, v10
	s_nop 1
	v_cndmask_b32_e64 v1, 0, 1, vcc
	v_cmp_ne_u32_e32 vcc, 0, v11
	s_nop 1
	v_addc_co_u32_e32 v0, vcc, v0, v1, vcc
	v_cmp_ne_u32_e32 vcc, 0, v12
	s_nop 1
	v_cndmask_b32_e64 v1, 0, 1, vcc
	v_cmp_ne_u32_e32 vcc, 0, v13
	s_nop 1
	v_addc_co_u32_e32 v0, vcc, v0, v1, vcc
	v_cmp_ne_u32_e32 vcc, 0, v14
	s_nop 1
	v_cndmask_b32_e64 v1, 0, 1, vcc
	v_cmp_ne_u32_e32 vcc, 0, v15
	s_nop 1
	v_addc_co_u32_e32 v0, vcc, v0, v1, vcc
	v_mov_b32_e32 v1, 0x12000
	v_max_u32_e32 v0, 1, v0
	ds_write_b32 v1, v2
	v_mov_b32_e32 v1, 0x12004
	ds_write_b32 v1, v0
	global_load_dwordx4 v[4:7], v161, s[96:97] offset:16 sc1
	global_load_dwordx4 v[8:11], v161, s[96:97] offset:32 sc1
	s_waitcnt vmcnt(0)
	v_add_u32_e32 v12, -1, v4
	v_and_b32_e32 v12, v12, v4
	v_add_u32_e32 v13, -1, v5
	v_and_or_b32 v12, v13, v5, v12
	v_add_u32_e32 v13, -1, v6
	v_and_or_b32 v12, v13, v6, v12
	v_add_u32_e32 v13, -1, v7
	v_and_or_b32 v12, v13, v7, v12
	v_add_u32_e32 v13, -1, v8
	v_and_or_b32 v12, v13, v8, v12
	v_add_u32_e32 v13, -1, v9
	v_and_or_b32 v12, v13, v9, v12
	v_add_u32_e32 v13, -1, v10
	v_and_or_b32 v12, v13, v10, v12
	v_add_u32_e32 v13, -1, v11
	v_and_or_b32 v12, v13, v11, v12
	v_cmp_eq_u32_e32 vcc, 0, v12
	v_mov_b32_e32 v13, 0x12008
	s_nop 0
	v_cndmask_b32_e64 v12, 0, 1, vcc
	ds_write_b32 v13, v12

.LBB0_2121:
	s_andn2_saveexec_b64 s[6:7], s[6:7]
	s_cbranch_execz .LBB0_2141
	s_mov_b64 s[6:7], exec
	v_mov_b32_e32 v1, 0x12008
	ds_read_b32 v1, v1
	s_waitcnt lgkmcnt(0)
	v_readfirstlane_b32 s8, v1
	s_cmp_lg_u32 s8, 0
	s_cbranch_scc1 .Lxl_6
	buffer_wbl2 sc1
	s_waitcnt lgkmcnt(0)
	s_waitcnt vmcnt(0)
	v_mbcnt_lo_u32_b32 v1, s6, 0
	v_mbcnt_hi_u32_b32 v1, s7, v1
	v_cmp_eq_u32_e32 vcc, 0, v1
	s_and_saveexec_b64 s[8:9], vcc
	s_cbranch_execz .LBB0_2124
	s_bcnt1_i32_b64 s6, s[6:7]
	v_mov_b32_e32 v2, s6
	v_readlane_b32 s6, v252, 18
	v_readlane_b32 s7, v252, 19
	s_nop 4
	global_atomic_add v2, v161, v2, s[6:7] sc0

.LBB0_2138:
.Lxl_6:
	s_or_b64 exec, exec, s[6:7]
	s_mov_b64 s[6:7], exec
	v_mbcnt_lo_u32_b32 v0, s6, 0
	v_mbcnt_hi_u32_b32 v0, s7, v0
	v_cmp_eq_u32_e32 vcc, 0, v0
	s_waitcnt vmcnt(0)
	buffer_inv sc1
	s_and_saveexec_b64 s[8:9], vcc
	s_cbranch_execz .LBB0_2140
	s_bcnt1_i32_b64 s6, s[6:7]
	v_mov_b32_e32 v0, s6
	global_atomic_add v191, v0, s[4:5] offset:1024

.LBB0_2206:
	v_bfe_u32 v64, v16, 5, 6
	v_and_b32_e32 v65, 3, v16
	v_lshl_or_b32 v64, v64, 2, v65
	v_bfe_u32 v65, v16, 11, 3
	v_lshl_or_b32 v64, v65, 8, v64
	v_bfe_u32 v65, v16, 2, 3
	v_lshl_or_b32 v64, v65, 11, v64
	v_mov_b32_e32 v65, 0
	v_ashrrev_i32_e32 v17, 31, v16
	s_waitcnt vmcnt(20)
	v_lshlrev_b64 v[28:29], 12, v[64:65]
	s_waitcnt vmcnt(15)
	v_lshl_add_u64 v[40:41], v[18:19], 0, v[28:29]
	v_lshlrev_b64 v[28:29], 11, v[64:65]
	s_waitcnt vmcnt(14)
	v_lshl_add_u64 v[44:45], v[20:21], 0, v[28:29]
	global_load_dwordx4 v[28:31], v[40:41], off
	global_load_dwordx4 v[32:35], v[40:41], off offset:1024
	global_load_dwordx4 v[56:59], v[40:41], off offset:2048
	global_load_dwordx4 v[60:63], v[40:41], off offset:3072
	v_add_u32_e32 v16, s40, v16
	s_waitcnt vmcnt(3)
	v_mov_b32_e32 v46, v29
	s_waitcnt vmcnt(2)
	v_mov_b32_e32 v47, v33
	v_mov_b32_e32 v42, v28
	v_mov_b32_e32 v43, v32
	v_pk_mul_f32 v[46:47], v[46:47], v[46:47]
	v_mov_b32_e32 v36, v30
	v_mov_b32_e32 v37, v34
	v_pk_fma_f32 v[42:43], v[42:43], v[42:43], v[46:47]
	v_mov_b32_e32 v38, v31
	v_mov_b32_e32 v39, v35
	v_pk_fma_f32 v[36:37], v[36:37], v[36:37], v[42:43]
	s_nop 0
	v_pk_fma_f32 v[46:47], v[38:39], v[38:39], v[36:37]
	v_add_f32_e32 v17, v46, v47
	s_waitcnt vmcnt(1)
	v_mov_b32_e32 v54, v57
	s_waitcnt vmcnt(0)
	v_mov_b32_e32 v55, v61
	v_mov_b32_e32 v52, v56
	v_mov_b32_e32 v53, v60
	v_pk_mul_f32 v[54:55], v[54:55], v[54:55]
	v_mov_b32_e32 v48, v58
	v_mov_b32_e32 v49, v62
	v_pk_fma_f32 v[52:53], v[52:53], v[52:53], v[54:55]
	v_mov_b32_e32 v50, v59
	v_mov_b32_e32 v51, v63
	v_pk_fma_f32 v[48:49], v[48:49], v[48:49], v[52:53]
	s_nop 0
	v_pk_fma_f32 v[48:49], v[50:51], v[50:51], v[48:49]
	s_nop 0
	v_add_f32_e32 v17, v17, v48
	v_add_f32_e32 v17, v17, v49
	ds_bpermute_b32 v46, v22, v17
	s_waitcnt lgkmcnt(0)
	v_add_f32_e32 v17, v17, v46
	ds_bpermute_b32 v46, v23, v17
	s_waitcnt lgkmcnt(0)
	v_add_f32_e32 v17, v17, v46
	ds_bpermute_b32 v46, v24, v17
	s_waitcnt lgkmcnt(0)
	v_add_f32_e32 v17, v17, v46
	ds_bpermute_b32 v46, v25, v17
	s_waitcnt lgkmcnt(0)
	v_add_f32_e32 v17, v17, v46
	ds_bpermute_b32 v46, v26, v17
	s_waitcnt lgkmcnt(0)
	v_add_f32_e32 v17, v17, v46
	ds_bpermute_b32 v46, v27, v17
	s_waitcnt lgkmcnt(0)
	v_add_f32_e32 v17, v17, v46
	v_fmamk_f32 v17, v17, 0x3a800000, v187
	v_cmp_gt_f32_e32 vcc, s79, v17
	v_mul_f32_e32 v46, 0x4b800000, v17
	s_nop 0
	v_cndmask_b32_e32 v17, v17, v46, vcc
	v_rsq_f32_e32 v17, v17
	s_nop 0
	v_mul_f32_e32 v46, 0x45800000, v17
	v_cndmask_b32_e32 v46, v17, v46, vcc
	v_pk_mul_f32 v[28:29], v[28:29], v[46:47] op_sel_hi:[1,0]
	v_pk_mul_f32 v[30:31], v[30:31], v[46:47] op_sel_hi:[1,0]
	v_pk_mul_f32 v[28:29], v[0:1], v[28:29]
	v_pk_mul_f32 v[30:31], v[2:3], v[30:31]
	v_cvt_pk_bf16_f32 v28, v28, v29
	v_cvt_pk_bf16_f32 v29, v30, v31
	global_store_dwordx2 v[44:45], v[28:29], off
	v_pk_mul_f32 v[28:29], v[32:33], v[46:47] op_sel_hi:[1,0]
	v_pk_mul_f32 v[30:31], v[34:35], v[46:47] op_sel_hi:[1,0]
	v_pk_mul_f32 v[28:29], v[4:5], v[28:29]
	v_pk_mul_f32 v[30:31], v[6:7], v[30:31]
	v_cvt_pk_bf16_f32 v28, v28, v29
	v_cvt_pk_bf16_f32 v29, v30, v31
	global_store_dwordx2 v[44:45], v[28:29], off offset:512
	v_pk_mul_f32 v[28:29], v[56:57], v[46:47] op_sel_hi:[1,0]
	v_pk_mul_f32 v[30:31], v[58:59], v[46:47] op_sel_hi:[1,0]
	v_pk_mul_f32 v[28:29], v[8:9], v[28:29]
	v_pk_mul_f32 v[30:31], v[10:11], v[30:31]
	v_cvt_pk_bf16_f32 v28, v28, v29
	v_cvt_pk_bf16_f32 v29, v30, v31
	global_store_dwordx2 v[44:45], v[28:29], off offset:1024
	v_pk_mul_f32 v[28:29], v[60:61], v[46:47] op_sel_hi:[1,0]
	v_pk_mul_f32 v[30:31], v[62:63], v[46:47] op_sel_hi:[1,0]
	v_pk_mul_f32 v[28:29], v[12:13], v[28:29]
	v_pk_mul_f32 v[30:31], v[14:15], v[30:31]
	v_cmp_lt_i32_e32 vcc, s34, v16
	v_cvt_pk_bf16_f32 v28, v28, v29
	v_cvt_pk_bf16_f32 v29, v30, v31
	s_or_b64 s[4:5], vcc, s[4:5]
	global_store_dwordx2 v[44:45], v[28:29], off offset:1536
	s_andn2_b64 exec, exec, s[4:5]
	s_cbranch_execnz .LBB0_2206

.LBB0_2375:
	s_andn2_saveexec_b64 s[4:5], s[4:5]
	s_cbranch_execz .LBB0_2395
	s_mov_b64 s[4:5], exec
	v_mov_b32_e32 v1, 0x12008
	ds_read_b32 v1, v1
	s_waitcnt lgkmcnt(0)
	v_readfirstlane_b32 s6, v1
	s_cmp_lg_u32 s6, 0
	s_cbranch_scc1 .Lxl_10
	buffer_wbl2 sc1
	s_waitcnt lgkmcnt(0)
	s_waitcnt vmcnt(0)
	v_mbcnt_lo_u32_b32 v1, s4, 0
	v_mbcnt_hi_u32_b32 v1, s5, v1
	v_cmp_eq_u32_e32 vcc, 0, v1
	s_and_saveexec_b64 s[6:7], vcc
	s_cbranch_execz .LBB0_2378
	s_bcnt1_i32_b64 s4, s[4:5]
	v_mov_b32_e32 v2, s4
	v_readlane_b32 s4, v252, 18
	v_readlane_b32 s5, v252, 19
	s_nop 4
	global_atomic_add v2, v161, v2, s[4:5] sc0

.LBB0_2392:
.Lxl_10:
	s_or_b64 exec, exec, s[4:5]
	s_mov_b64 s[4:5], exec
	v_mbcnt_lo_u32_b32 v0, s4, 0
	v_mbcnt_hi_u32_b32 v0, s5, v0
	v_cmp_eq_u32_e32 vcc, 0, v0
	s_waitcnt vmcnt(0)
	buffer_inv sc1
	s_and_saveexec_b64 s[6:7], vcc
	s_cbranch_execz .LBB0_2394
	s_bcnt1_i32_b64 s4, s[4:5]
	v_mov_b32_e32 v0, s4
	global_atomic_add v191, v0, s[2:3] offset:1024

.LBB0_2397:
	v_bfe_u32 v64, v16, 5, 6
	v_and_b32_e32 v65, 3, v16
	v_lshl_or_b32 v64, v64, 2, v65
	v_bfe_u32 v65, v16, 11, 3
	v_lshl_or_b32 v64, v65, 8, v64
	v_bfe_u32 v65, v16, 2, 3
	v_lshl_or_b32 v64, v65, 11, v64
	v_mov_b32_e32 v65, 0
	v_ashrrev_i32_e32 v17, 31, v16
	s_waitcnt vmcnt(20)
	v_lshlrev_b64 v[28:29], 12, v[64:65]
	s_waitcnt vmcnt(15)
	v_lshl_add_u64 v[40:41], v[18:19], 0, v[28:29]
	v_lshlrev_b64 v[28:29], 11, v[64:65]
	s_waitcnt vmcnt(14)
	v_lshl_add_u64 v[44:45], v[20:21], 0, v[28:29]
	global_load_dwordx4 v[28:31], v[40:41], off
	global_load_dwordx4 v[32:35], v[40:41], off offset:1024
	global_load_dwordx4 v[56:59], v[40:41], off offset:2048
	global_load_dwordx4 v[60:63], v[40:41], off offset:3072
	v_add_u32_e32 v16, s40, v16
	s_waitcnt vmcnt(3)
	v_mov_b32_e32 v46, v29
	s_waitcnt vmcnt(2)
	v_mov_b32_e32 v47, v33
	v_mov_b32_e32 v42, v28
	v_mov_b32_e32 v43, v32
	v_pk_mul_f32 v[46:47], v[46:47], v[46:47]
	v_mov_b32_e32 v36, v30
	v_mov_b32_e32 v37, v34
	v_pk_fma_f32 v[42:43], v[42:43], v[42:43], v[46:47]
	v_mov_b32_e32 v38, v31
	v_mov_b32_e32 v39, v35
	v_pk_fma_f32 v[36:37], v[36:37], v[36:37], v[42:43]
	s_nop 0
	v_pk_fma_f32 v[46:47], v[38:39], v[38:39], v[36:37]
	v_add_f32_e32 v17, v46, v47
	s_waitcnt vmcnt(1)
	v_mov_b32_e32 v54, v57
	s_waitcnt vmcnt(0)
	v_mov_b32_e32 v55, v61
	v_mov_b32_e32 v52, v56
	v_mov_b32_e32 v53, v60
	v_pk_mul_f32 v[54:55], v[54:55], v[54:55]
	v_mov_b32_e32 v48, v58
	v_mov_b32_e32 v49, v62
	v_pk_fma_f32 v[52:53], v[52:53], v[52:53], v[54:55]
	v_mov_b32_e32 v50, v59
	v_mov_b32_e32 v51, v63
	v_pk_fma_f32 v[48:49], v[48:49], v[48:49], v[52:53]
	s_nop 0
	v_pk_fma_f32 v[48:49], v[50:51], v[50:51], v[48:49]
	s_nop 0
	v_add_f32_e32 v17, v17, v48
	v_add_f32_e32 v17, v17, v49
	ds_bpermute_b32 v46, v22, v17
	s_waitcnt lgkmcnt(0)
	v_add_f32_e32 v17, v17, v46
	ds_bpermute_b32 v46, v23, v17
	s_waitcnt lgkmcnt(0)
	v_add_f32_e32 v17, v17, v46
	ds_bpermute_b32 v46, v24, v17
	s_waitcnt lgkmcnt(0)
	v_add_f32_e32 v17, v17, v46
	ds_bpermute_b32 v46, v25, v17
	s_waitcnt lgkmcnt(0)
	v_add_f32_e32 v17, v17, v46
	ds_bpermute_b32 v46, v26, v17
	s_waitcnt lgkmcnt(0)
	v_add_f32_e32 v17, v17, v46
	ds_bpermute_b32 v46, v27, v17
	s_waitcnt lgkmcnt(0)
	v_add_f32_e32 v17, v17, v46
	v_fmamk_f32 v17, v17, 0x3a800000, v187
	v_cmp_gt_f32_e32 vcc, s79, v17
	v_mul_f32_e32 v46, 0x4b800000, v17
	s_nop 0
	v_cndmask_b32_e32 v17, v17, v46, vcc
	v_rsq_f32_e32 v17, v17
	s_nop 0
	v_mul_f32_e32 v46, 0x45800000, v17
	v_cndmask_b32_e32 v46, v17, v46, vcc
	v_pk_mul_f32 v[28:29], v[28:29], v[46:47] op_sel_hi:[1,0]
	v_pk_mul_f32 v[30:31], v[30:31], v[46:47] op_sel_hi:[1,0]
	v_pk_mul_f32 v[28:29], v[0:1], v[28:29]
	v_pk_mul_f32 v[30:31], v[2:3], v[30:31]
	v_cvt_pk_bf16_f32 v28, v28, v29
	v_cvt_pk_bf16_f32 v29, v30, v31
	global_store_dwordx2 v[44:45], v[28:29], off
	v_pk_mul_f32 v[28:29], v[32:33], v[46:47] op_sel_hi:[1,0]
	v_pk_mul_f32 v[30:31], v[34:35], v[46:47] op_sel_hi:[1,0]
	v_pk_mul_f32 v[28:29], v[4:5], v[28:29]
	v_pk_mul_f32 v[30:31], v[6:7], v[30:31]
	v_cvt_pk_bf16_f32 v28, v28, v29
	v_cvt_pk_bf16_f32 v29, v30, v31
	global_store_dwordx2 v[44:45], v[28:29], off offset:512
	v_pk_mul_f32 v[28:29], v[56:57], v[46:47] op_sel_hi:[1,0]
	v_pk_mul_f32 v[30:31], v[58:59], v[46:47] op_sel_hi:[1,0]
	v_pk_mul_f32 v[28:29], v[8:9], v[28:29]
	v_pk_mul_f32 v[30:31], v[10:11], v[30:31]
	v_cvt_pk_bf16_f32 v28, v28, v29
	v_cvt_pk_bf16_f32 v29, v30, v31
	global_store_dwordx2 v[44:45], v[28:29], off offset:1024
	v_pk_mul_f32 v[28:29], v[60:61], v[46:47] op_sel_hi:[1,0]
	v_pk_mul_f32 v[30:31], v[62:63], v[46:47] op_sel_hi:[1,0]
	v_pk_mul_f32 v[28:29], v[12:13], v[28:29]
	v_pk_mul_f32 v[30:31], v[14:15], v[30:31]
	v_cmp_lt_i32_e32 vcc, s34, v16
	v_cvt_pk_bf16_f32 v28, v28, v29
	v_cvt_pk_bf16_f32 v29, v30, v31
	s_or_b64 s[2:3], vcc, s[2:3]
	global_store_dwordx2 v[44:45], v[28:29], off offset:1536
	s_andn2_b64 exec, exec, s[2:3]
	s_cbranch_execnz .LBB0_2397
